# grid barrier: single early L2 write-back by the arriver with 20 WGs of its XCD still to come
# baseline (speedup 1.0000x reference)
; __device__ __forceinline__ unsigned xb_ld(unsigned* p)              { return __hip_atomic_load(p, __ATOMIC_RELAXED, __HIP_MEMORY_SCOPE_AGENT); }
; __device__ __forceinline__ unsigned xb_add(unsigned* p, unsigned v) { return __hip_atomic_fetch_add(p, v, __ATOMIC_RELAXED, __HIP_MEMORY_SCOPE_AGENT); }
; #define XB_SPIN(cond, bar) do { unsigned _sp = 0; while (cond) { __builtin_amdgcn_s_sleep(1); \
;     if ((++_sp & 255u) == 0u) { if (xb_ld(&(bar)[XB_TMO])) break; if (_sp > XB_SPIN_CAP) { atomicAdd(&(bar)[XB_TMO], 1u); break; } } } } while (0)
; __device__ __forceinline__ void xcd_barrier(const XcdBarrier& b) {
;     ...
;         const unsigned old = xb_add(&bar[XB_XSUB(b.x)], 1u);
;         const unsigned gen = old / nloc;
;         if (old + 1u == (gen + 1u) * nloc) {
;             __builtin_amdgcn_fence(__ATOMIC_RELEASE, "agent");
;             asm volatile("s_waitcnt vmcnt(0)" ::: "memory");
;             const unsigned og = xb_add(&bar[XB_TOP], 1u);
;             const unsigned tg = og / nx;
;             __builtin_amdgcn_fence(__ATOMIC_ACQUIRE, "agent");
;             if (og + 1u == (tg + 1u) * nx) xb_add(&bar[XB_TOPGEN], 1u);
;             else XB_SPIN(xb_ld(&bar[XB_TOPGEN]) == tg, bar);
;             xb_add(&bar[XB_XGEN(b.x)], 1u);
;             asm volatile("s_waitcnt vmcnt(0)" ::: "memory");
;         } else {
;             __builtin_amdgcn_fence(__ATOMIC_ACQUIRE, "agent");
;             XB_SPIN(xb_ld(&bar[XB_XGEN(b.x)]) == gen, bar);
.Lgd_notlast_0:
	s_sub_u32 s24, s25, s24
	s_cmp_eq_u32 s24, 20
	s_cbranch_scc1 .Lgd_early_0
	s_cmp_lg_u32 s24, 9999
	s_cbranch_scc1 .Lgd_join_0
.Lgd_early_0:
	buffer_wbl2 sc1
